# selected-branch and window attention: fixed softmax shift M folded into the QK^T accumulator init (C=-M), 32 v_sub per key tile removed
# speedup vs baseline: 1.0068x; 1.0004x over previous
.LBB0_528:
	s_or_b64 exec, exec, s[0:1]
	v_readfirstlane_b32 s4, v0
	s_cmpk_gt_i32 s4, 0x17f
	s_mov_b64 s[0:1], -1
	s_cbranch_scc1 .LBB0_523
	s_cmpk_gt_i32 s4, 0x7f
	s_cbranch_scc0 .LBB0_536
	global_load_dword v0, v[146:147], off
	global_load_dword v1, v[146:147], off offset:768
	v_and_b32_e32 v2, 64, v226
	v_xor_b32_e32 v3, 1, v226
	v_add_u32_e32 v2, 64, v2
	v_xor_b32_e32 v32, 2, v226
	v_cmp_lt_i32_e32 vcc, v3, v2
	v_xor_b32_e32 v33, 4, v226
	v_xor_b32_e32 v34, 8, v226
	v_cndmask_b32_e32 v3, v226, v3, vcc
	v_cmp_lt_i32_e32 vcc, v32, v2
	v_xor_b32_e32 v35, 16, v226
	v_xor_b32_e32 v36, 32, v226
	v_cndmask_b32_e32 v32, v226, v32, vcc
	v_cmp_lt_i32_e32 vcc, v33, v2
	v_lshlrev_b32_e32 v3, 2, v3
	v_lshlrev_b32_e32 v32, 2, v32
	v_cndmask_b32_e32 v33, v226, v33, vcc
	v_cmp_lt_i32_e32 vcc, v34, v2
	v_lshlrev_b32_e32 v33, 2, v33
	s_add_i32 s0, s4, 0xffffff80
	v_cndmask_b32_e32 v34, v226, v34, vcc
	v_cmp_lt_i32_e32 vcc, v35, v2
	v_lshlrev_b32_e32 v34, 2, v34
	s_lshl_b32 s3, s0, 4
	v_cndmask_b32_e32 v35, v226, v35, vcc
	v_cmp_lt_i32_e32 vcc, v36, v2
	s_and_b32 s6, s3, 0x7fffffe0
	v_or_b32_e32 v185, s6, v202
	v_cndmask_b32_e32 v2, v226, v36, vcc
	v_lshlrev_b32_e32 v184, 2, v2
	v_lshl_add_u32 v2, v185, 8, s74
	v_lshlrev_b32_e32 v180, 1, v2
	v_lshlrev_b32_e32 v35, 2, v35
	s_lshl_b32 s1, s4, 6
	s_and_b32 s1, s1, 64
	s_or_b32 s5, s1, s19
	s_add_i32 s1, s6, 0xfffffe01
	s_ashr_i32 s1, s1, 6
	s_cmp_gt_u32 s0, 31
	v_mov_b32_e32 v31, 0
	s_cselect_b32 s38, s1, 0
	s_lshr_b32 s7, s0, 2
	v_mov_b32_e32 v30, v31
	v_mov_b32_e32 v29, v31
	v_mov_b32_e32 v28, v31
	v_mov_b32_e32 v27, v31
	v_mov_b32_e32 v26, v31
	v_mov_b32_e32 v25, v31
	v_mov_b32_e32 v24, v31
	v_mov_b32_e32 v23, v31
	v_mov_b32_e32 v22, v31
	v_mov_b32_e32 v21, v31
	v_mov_b32_e32 v20, v31
	v_mov_b32_e32 v19, v31
	v_mov_b32_e32 v18, v31
	v_mov_b32_e32 v17, v31
	v_mov_b32_e32 v16, v31
	v_mov_b32_e32 v15, v31
	v_mov_b32_e32 v14, v31
	v_mov_b32_e32 v13, v31
	v_mov_b32_e32 v12, v31
	v_mov_b32_e32 v11, v31
	v_mov_b32_e32 v10, v31
	v_mov_b32_e32 v9, v31
	v_mov_b32_e32 v8, v31
	v_mov_b32_e32 v7, v31
	v_mov_b32_e32 v6, v31
	v_mov_b32_e32 v5, v31
	v_mov_b32_e32 v4, v31
	s_cmp_gt_i32 s38, s7
	v_mov_b32_e32 v163, v31
	s_waitcnt vmcnt(1)
	v_and_b32_e32 v36, 0x7fffffff, v0
	s_waitcnt vmcnt(0)
	v_and_b32_e32 v37, 0x7fffffff, v1
	ds_bpermute_b32 v36, v3, v36
	ds_bpermute_b32 v3, v3, v37
	v_max_f32_e64 v0, |v0|, |v0|
	v_max_f32_e64 v1, |v1|, |v1|
	s_waitcnt lgkmcnt(1)
	v_max_f32_e32 v36, v36, v36
	s_waitcnt lgkmcnt(0)
	v_max_f32_e32 v3, v3, v3
	v_max_f32_e32 v0, v0, v36
	v_max_f32_e32 v1, v1, v3
	ds_bpermute_b32 v3, v32, v0
	ds_bpermute_b32 v32, v32, v1
	s_waitcnt lgkmcnt(1)
	v_max_f32_e32 v3, v3, v3
	s_waitcnt lgkmcnt(0)
	v_max_f32_e32 v32, v32, v32
	v_max_f32_e32 v0, v0, v3
	v_max_f32_e32 v1, v1, v32
	ds_bpermute_b32 v3, v33, v0
	ds_bpermute_b32 v32, v33, v1
	s_waitcnt lgkmcnt(1)
	v_max_f32_e32 v3, v3, v3
	s_waitcnt lgkmcnt(0)
	v_max_f32_e32 v32, v32, v32
	v_max_f32_e32 v0, v0, v3
	v_max_f32_e32 v1, v1, v32
	ds_bpermute_b32 v3, v34, v0
	ds_bpermute_b32 v32, v34, v1
	s_waitcnt lgkmcnt(1)
	v_max_f32_e32 v2, v3, v3
	s_waitcnt lgkmcnt(0)
	v_max_f32_e32 v3, v32, v32
	v_max_f32_e32 v0, v0, v2
	v_max_f32_e32 v1, v1, v3
	ds_bpermute_b32 v2, v35, v0
	ds_bpermute_b32 v3, v35, v1
	s_waitcnt lgkmcnt(1)
	v_max_f32_e32 v2, v2, v2
	s_waitcnt lgkmcnt(0)
	v_max_f32_e32 v3, v3, v3
	v_max_f32_e32 v33, v0, v2
	v_max_f32_e32 v32, v1, v3
	ds_bpermute_b32 v35, v184, v33
	ds_bpermute_b32 v34, v184, v32
	v_mov_b32_e32 v3, v31
	v_mov_b32_e32 v2, v31
	v_mov_b32_e32 v1, v31
	v_mov_b32_e32 v0, v31
	s_cbranch_scc1 .LBB0_535
	v_mov_b32_e32 v181, v65
	v_lshl_add_u64 v[0:1], s[52:53], 0, v[180:181]
	s_lshl_b32 s50, s5, 1
	v_lshl_add_u64 v[0:1], v[0:1], 0, s[50:51]
	v_mov_b32_e32 v163, v65
	s_ashr_i32 s39, s38, 31
	v_lshl_add_u64 v[0:1], v[0:1], 0, v[162:163]
	s_lshl_b64 s[0:1], s[38:39], 13
	global_load_dwordx4 v[66:69], v[0:1], off
	global_load_dwordx4 v[70:73], v[0:1], off offset:32
	global_load_dwordx4 v[74:77], v[0:1], off offset:64
	global_load_dwordx4 v[78:81], v[0:1], off offset:96
	v_lshl_add_u64 v[0:1], v[166:167], 0, s[0:1]
	v_add_co_u32_e32 v2, vcc, s77, v0
	v_mov_b32_e32 v163, 0
	s_nop 0
	v_addc_co_u32_e32 v3, vcc, 0, v1, vcc
	global_load_dwordx4 v[82:85], v[2:3], off offset:3072
	global_load_dwordx4 v[86:89], v[2:3], off offset:2048
	global_load_dwordx4 v[94:97], v[0:1], off offset:3072
	global_load_dwordx4 v[98:101], v[0:1], off offset:2048
	global_load_dwordx4 v[90:93], v[2:3], off offset:1024
	global_load_dwordx4 v[106:109], v[2:3], off
	global_load_dwordx4 v[102:105], v[0:1], off offset:1024
	global_load_dwordx4 v[110:113], v[0:1], off
	s_waitcnt lgkmcnt(1)
	v_max_f32_e32 v0, v35, v35
	v_max_f32_e32 v1, v33, v33
	v_max_f32_e32 v0, v1, v0
	s_waitcnt lgkmcnt(0)
	v_max_f32_e32 v1, v34, v34
	v_max_f32_e32 v2, v32, v32
	v_max_f32_e32 v1, v2, v1
	v_mul_f32_e32 v0, 0x413c5bb7, v0
	v_fmaak_f32 v181, v0, v1, 0x3d4ccccd
	v_sub_f32_e32 v232, 0, v181
	v_mov_b32_e32 v233, v232
	v_mov_b32_e32 v234, v232
	v_mov_b32_e32 v235, v232
	v_mov_b32_e32 v236, v232
	v_mov_b32_e32 v237, v232
	v_mov_b32_e32 v238, v232
	v_mov_b32_e32 v239, v232
	v_mov_b32_e32 v240, v232
	v_mov_b32_e32 v241, v232
	v_mov_b32_e32 v242, v232
	v_mov_b32_e32 v243, v232
	v_mov_b32_e32 v244, v232
	v_mov_b32_e32 v245, v232
	v_mov_b32_e32 v246, v232
	v_mov_b32_e32 v247, v232
	s_add_i32 s13, s6, 0xfffffe1f
	v_lshl_add_u64 v[182:183], v[178:179], 0, s[0:1]
	s_lshl_b32 s22, s38, 6
	v_mov_b32_e32 v16, 0
	v_mov_b32_e32 v17, v163
	v_mov_b32_e32 v18, v163
	v_mov_b32_e32 v19, v163
	v_mov_b32_e32 v20, v163
	v_mov_b32_e32 v21, v163
	v_mov_b32_e32 v22, v163
	v_mov_b32_e32 v23, v163
	v_mov_b32_e32 v24, v163
	v_mov_b32_e32 v25, v163
	v_mov_b32_e32 v26, v163
	v_mov_b32_e32 v27, v163
	v_mov_b32_e32 v28, v163
	v_mov_b32_e32 v29, v163
	v_mov_b32_e32 v30, v163
	v_mov_b32_e32 v31, v163
	v_mov_b32_e32 v0, 0
	v_mov_b32_e32 v1, v163
	v_mov_b32_e32 v2, v163
	v_mov_b32_e32 v3, v163
	v_mov_b32_e32 v4, v163
	v_mov_b32_e32 v5, v163
	v_mov_b32_e32 v6, v163
	v_mov_b32_e32 v7, v163
	v_mov_b32_e32 v8, v163
	v_mov_b32_e32 v9, v163
	v_mov_b32_e32 v10, v163
	v_mov_b32_e32 v11, v163
	v_mov_b32_e32 v12, v163
	v_mov_b32_e32 v13, v163
	v_mov_b32_e32 v14, v163
	v_mov_b32_e32 v15, v163
	s_branch .LBB0_533
.LBB0_532:
	s_nop 10
	v_exp_f32_e32 v189, v32
	v_exp_f32_e32 v188, v48
	v_exp_f32_e32 v64, v49
	v_exp_f32_e32 v48, v33
	v_add_f32_e32 v49, v189, v188
	v_lshl_add_u64 v[182:183], v[182:183], 0, s[78:79]
	s_andn2_b64 vcc, exec, s[46:47]
	v_pk_add_f32 v[32:33], v[48:49], v[64:65]
	s_add_i32 s22, s22, 64
	v_pk_add_f32 v[186:187], v[32:33], v[32:33] op_sel_hi:[0,1]
	v_exp_f32_e32 v49, v50
	v_exp_f32_e32 v190, v34
	v_exp_f32_e32 v186, v51
	v_exp_f32_e32 v50, v35
	v_add_f32_e32 v51, v190, v49
	v_pk_add_f32 v[32:33], v[50:51], v[186:187]
	s_nop 0
	v_pk_add_f32 v[34:35], v[32:33], v[32:33] op_sel_hi:[0,1]
	v_exp_f32_e32 v51, v52
	v_exp_f32_e32 v187, v36
	v_exp_f32_e32 v34, v53
	v_exp_f32_e32 v36, v37
	v_add_f32_e32 v37, v187, v51
	v_pk_add_f32 v[32:33], v[36:37], v[34:35]
	s_nop 0
	v_pk_add_f32 v[52:53], v[32:33], v[32:33] op_sel_hi:[0,1]
	v_exp_f32_e32 v35, v54
	v_exp_f32_e32 v37, v38
	v_exp_f32_e32 v52, v55
	v_exp_f32_e32 v38, v39
	v_add_f32_e32 v39, v37, v35
	v_cvt_pk_bf16_f32 v34, v51, v34
	v_cvt_pk_bf16_f32 v35, v35, v52
	v_pk_add_f32 v[32:33], v[38:39], v[52:53]
	s_nop 0
	v_pk_add_f32 v[54:55], v[32:33], v[32:33] op_sel_hi:[0,1]
	v_exp_f32_e32 v39, v56
	v_exp_f32_e32 v191, v40
	v_exp_f32_e32 v54, v57
	v_exp_f32_e32 v40, v41
	v_add_f32_e32 v41, v191, v39
	v_pk_add_f32 v[32:33], v[40:41], v[54:55]
	s_nop 0
	v_pk_add_f32 v[56:57], v[32:33], v[32:33] op_sel_hi:[0,1]
	v_exp_f32_e32 v41, v58
	v_exp_f32_e32 v55, v42
	v_exp_f32_e32 v56, v59
	v_exp_f32_e32 v42, v43
	v_add_f32_e32 v43, v55, v41
	v_pk_add_f32 v[32:33], v[42:43], v[56:57]
	s_nop 0
	v_pk_add_f32 v[58:59], v[32:33], v[32:33] op_sel_hi:[0,1]
	v_exp_f32_e32 v43, v60
	v_exp_f32_e32 v57, v44
	v_exp_f32_e32 v58, v61
	v_exp_f32_e32 v44, v45
	v_cvt_pk_bf16_f32 v32, v188, v64
	v_cvt_pk_bf16_f32 v33, v49, v186
	v_add_f32_e32 v45, v57, v43
	v_pk_add_f32 v[52:53], v[44:45], v[58:59]
	s_waitcnt vmcnt(15)
	v_mfma_f32_32x32x16_bf16 v[16:31], v[142:145], v[32:35], v[16:31]
	v_pk_add_f32 v[52:53], v[52:53], v[52:53] op_sel_hi:[0,1]
	v_exp_f32_e32 v45, v62
	s_waitcnt vmcnt(14)
	v_mfma_f32_32x32x16_bf16 v[0:15], v[138:141], v[32:35], v[0:15]
	v_exp_f32_e32 v52, v63
	v_cvt_pk_bf16_f32 v32, v39, v54
	v_cvt_pk_bf16_f32 v33, v41, v56
	v_cvt_pk_bf16_f32 v34, v43, v58
	v_cvt_pk_bf16_f32 v35, v45, v52
	s_waitcnt vmcnt(13)
	s_nop 0
	v_mfma_f32_32x32x16_bf16 v[16:31], v[134:137], v[32:35], v[16:31]
	s_waitcnt vmcnt(12)
	v_mfma_f32_32x32x16_bf16 v[0:15], v[130:133], v[32:35], v[0:15]
	v_cvt_pk_bf16_f32 v32, v189, v48
	v_cvt_pk_bf16_f32 v33, v190, v50
	v_cvt_pk_bf16_f32 v34, v187, v36
	v_cvt_pk_bf16_f32 v35, v37, v38
	v_exp_f32_e32 v37, v46
	s_waitcnt vmcnt(11)
	v_mfma_f32_32x32x16_bf16 v[16:31], v[126:129], v[32:35], v[16:31]
	s_waitcnt vmcnt(10)
	v_mfma_f32_32x32x16_bf16 v[0:15], v[122:125], v[32:35], v[0:15]
	v_exp_f32_e32 v36, v47
	v_cvt_pk_bf16_f32 v32, v191, v40
	v_cvt_pk_bf16_f32 v33, v55, v42
	v_cvt_pk_bf16_f32 v34, v57, v44
	v_cvt_pk_bf16_f32 v35, v37, v36
	v_add_f32_e32 v37, v37, v45
	v_pk_add_f32 v[36:37], v[36:37], v[52:53]
	s_waitcnt vmcnt(9)
	v_mfma_f32_32x32x16_bf16 v[16:31], v[118:121], v[32:35], v[16:31]
	v_add_f32_e32 v36, v36, v37
	v_add_f32_e32 v163, v163, v36
	s_waitcnt vmcnt(8)
	v_mfma_f32_32x32x16_bf16 v[0:15], v[114:117], v[32:35], v[0:15]
	s_cbranch_vccz .LBB0_535
.LBB0_533:
	s_waitcnt vmcnt(0)
	v_mfma_f32_32x32x16_bf16 v[48:63], v[110:113], v[66:69], v[232:247]
	s_cmp_ge_i32 s38, s7
	s_mov_b32 s0, s38
	s_cselect_b64 s[46:47], -1, 0
	s_add_i32 s38, s38, 1
	s_cmp_lt_i32 s0, s7
	v_mov_b64_e32 v[192:193], v[84:85]
	s_cselect_b32 s0, s38, s0
	v_mfma_f32_32x32x16_bf16 v[32:47], v[106:109], v[66:69], v[232:247]
	v_mov_b64_e32 v[190:191], v[82:83]
	v_add_co_u32_e32 v82, vcc, s77, v182
	s_ashr_i32 s1, s0, 31
	s_nop 0
	v_addc_co_u32_e32 v83, vcc, 0, v183, vcc
	s_lshl_b64 s[0:1], s[0:1], 13
	v_mfma_f32_32x32x16_bf16 v[48:63], v[102:105], v[70:73], v[48:63]
	global_load_dwordx4 v[142:145], v[182:183], off
	global_load_dwordx4 v[138:141], v[182:183], off offset:1024
	global_load_dwordx4 v[134:137], v[182:183], off offset:2048
	global_load_dwordx4 v[130:133], v[182:183], off offset:3072
	global_load_dwordx4 v[126:129], v[82:83], off
	global_load_dwordx4 v[122:125], v[82:83], off offset:1024
	global_load_dwordx4 v[118:121], v[82:83], off offset:2048
	global_load_dwordx4 v[114:117], v[82:83], off offset:3072
	v_lshl_add_u64 v[82:83], v[166:167], 0, s[0:1]
	v_mov_b64_e32 v[188:189], v[96:97]
	v_add_co_u32_e32 v84, vcc, s77, v82
	v_mov_b64_e32 v[186:187], v[94:95]
	v_mfma_f32_32x32x16_bf16 v[32:47], v[90:93], v[70:73], v[32:47]
	v_addc_co_u32_e32 v85, vcc, 0, v83, vcc
	s_add_i32 s0, s22, 63
	s_cmp_le_i32 s0, s6
	s_cselect_b64 s[0:1], -1, 0
	s_cmp_gt_i32 s22, s13
	s_cselect_b64 s[24:25], -1, 0
	v_mfma_f32_32x32x16_bf16 v[48:63], v[98:101], v[74:77], v[48:63]
	global_load_dwordx4 v[110:113], v[82:83], off
	global_load_dwordx4 v[102:105], v[82:83], off offset:1024
	global_load_dwordx4 v[106:109], v[84:85], off
	global_load_dwordx4 v[90:93], v[84:85], off offset:1024
	global_load_dwordx4 v[98:101], v[82:83], off offset:2048
	global_load_dwordx4 v[94:97], v[82:83], off offset:3072
	s_and_b64 s[0:1], s[0:1], s[24:25]
	s_and_b64 vcc, exec, s[0:1]
	v_mfma_f32_32x32x16_bf16 v[32:47], v[86:89], v[74:77], v[32:47]
	global_load_dwordx4 v[86:89], v[84:85], off offset:2048
	s_nop 0
	global_load_dwordx4 v[82:85], v[84:85], off offset:3072
	v_mfma_f32_32x32x16_bf16 v[48:63], v[186:189], v[78:81], v[48:63]
	v_mfma_f32_32x32x16_bf16 v[32:47], v[190:193], v[78:81], v[32:47]
	s_cbranch_vccnz .LBB0_532
	v_mov_b32_e32 v64, v185
	v_add_u32_e32 v186, s22, v148
	v_add_u32_e32 v188, 0xfffffe00, v64
	v_cmp_le_i32_e32 vcc, v186, v64
	v_cmp_gt_i32_e64 s[0:1], v186, v188
	v_add_u32_e32 v187, 32, v186
	s_and_b64 vcc, vcc, s[0:1]
	s_nop 2
	v_cndmask_b32_e32 v48, v214, v48, vcc
	v_cmp_le_i32_e32 vcc, v187, v64
	v_cmp_gt_i32_e64 s[0:1], v187, v188
	s_and_b64 vcc, vcc, s[0:1]
	v_cndmask_b32_e32 v32, v214, v32, vcc
	v_cmp_lt_i32_e32 vcc, v186, v64
	v_cmp_ge_i32_e64 s[0:1], v186, v188
	s_and_b64 vcc, vcc, s[0:1]
	v_cndmask_b32_e32 v49, v214, v49, vcc
	v_cmp_lt_i32_e32 vcc, v187, v64
	v_cmp_ge_i32_e64 s[0:1], v187, v188
	s_and_b64 vcc, vcc, s[0:1]
	v_add_u32_e32 v187, 2, v186
	v_cndmask_b32_e32 v33, v214, v33, vcc
	v_cmp_le_i32_e32 vcc, v187, v64
	v_cmp_gt_i32_e64 s[0:1], v187, v188
	v_add_u32_e32 v189, 34, v186
	s_and_b64 vcc, vcc, s[0:1]
	v_cndmask_b32_e32 v50, v214, v50, vcc
	v_cmp_le_i32_e32 vcc, v189, v64
	v_cmp_gt_i32_e64 s[0:1], v189, v188
	s_and_b64 vcc, vcc, s[0:1]
	v_add_u32_e32 v187, 3, v186
	v_cndmask_b32_e32 v34, v214, v34, vcc
	v_cmp_le_i32_e32 vcc, v187, v64
	v_cmp_gt_i32_e64 s[0:1], v187, v188
	v_add_u32_e32 v189, 35, v186
	s_and_b64 vcc, vcc, s[0:1]
	v_cndmask_b32_e32 v51, v214, v51, vcc
	v_cmp_le_i32_e32 vcc, v189, v64
	v_cmp_gt_i32_e64 s[0:1], v189, v188
	s_and_b64 vcc, vcc, s[0:1]
	v_add_u32_e32 v187, 8, v186
	v_cndmask_b32_e32 v35, v214, v35, vcc
	v_cmp_le_i32_e32 vcc, v187, v64
	v_cmp_gt_i32_e64 s[0:1], v187, v188
	v_add_u32_e32 v189, 40, v186
	s_and_b64 vcc, vcc, s[0:1]
	v_cndmask_b32_e32 v52, v214, v52, vcc
	v_cmp_le_i32_e32 vcc, v189, v64
	v_cmp_gt_i32_e64 s[0:1], v189, v188
	s_and_b64 vcc, vcc, s[0:1]
	v_add_u32_e32 v187, 9, v186
	v_cndmask_b32_e32 v36, v214, v36, vcc
	v_cmp_le_i32_e32 vcc, v187, v64
	v_cmp_gt_i32_e64 s[0:1], v187, v188
	v_add_u32_e32 v189, 41, v186
	s_and_b64 vcc, vcc, s[0:1]
	v_cndmask_b32_e32 v53, v214, v53, vcc
	v_cmp_le_i32_e32 vcc, v189, v64
	v_cmp_gt_i32_e64 s[0:1], v189, v188
	s_and_b64 vcc, vcc, s[0:1]
	v_add_u32_e32 v187, 10, v186
	v_cndmask_b32_e32 v37, v214, v37, vcc
	v_cmp_le_i32_e32 vcc, v187, v64
	v_cmp_gt_i32_e64 s[0:1], v187, v188
	v_add_u32_e32 v189, 42, v186
	s_and_b64 vcc, vcc, s[0:1]
	v_cndmask_b32_e32 v54, v214, v54, vcc
	v_cmp_le_i32_e32 vcc, v189, v64
	v_cmp_gt_i32_e64 s[0:1], v189, v188
	s_and_b64 vcc, vcc, s[0:1]
	v_add_u32_e32 v187, 11, v186
	v_cndmask_b32_e32 v38, v214, v38, vcc
	v_cmp_le_i32_e32 vcc, v187, v64
	v_cmp_gt_i32_e64 s[0:1], v187, v188
	v_add_u32_e32 v189, 43, v186
	s_and_b64 vcc, vcc, s[0:1]
	v_cndmask_b32_e32 v55, v214, v55, vcc
	v_cmp_le_i32_e32 vcc, v189, v64
	v_cmp_gt_i32_e64 s[0:1], v189, v188
	s_and_b64 vcc, vcc, s[0:1]
	v_add_u32_e32 v187, 16, v186
	v_cndmask_b32_e32 v39, v214, v39, vcc
	v_cmp_le_i32_e32 vcc, v187, v64
	v_cmp_gt_i32_e64 s[0:1], v187, v188
	v_add_u32_e32 v189, 48, v186
	s_and_b64 vcc, vcc, s[0:1]
	v_cndmask_b32_e32 v56, v214, v56, vcc
	v_cmp_le_i32_e32 vcc, v189, v64
	v_cmp_gt_i32_e64 s[0:1], v189, v188
	s_and_b64 vcc, vcc, s[0:1]
	v_add_u32_e32 v187, 17, v186
	v_cndmask_b32_e32 v40, v214, v40, vcc
	v_cmp_le_i32_e32 vcc, v187, v64
	v_cmp_gt_i32_e64 s[0:1], v187, v188
	v_add_u32_e32 v189, 49, v186
	s_and_b64 vcc, vcc, s[0:1]
	v_cndmask_b32_e32 v57, v214, v57, vcc
	v_cmp_le_i32_e32 vcc, v189, v64
	v_cmp_gt_i32_e64 s[0:1], v189, v188
	s_and_b64 vcc, vcc, s[0:1]
	v_add_u32_e32 v187, 18, v186
	v_cndmask_b32_e32 v41, v214, v41, vcc
	v_cmp_le_i32_e32 vcc, v187, v64
	v_cmp_gt_i32_e64 s[0:1], v187, v188
	v_add_u32_e32 v189, 50, v186
	s_and_b64 vcc, vcc, s[0:1]
	v_cndmask_b32_e32 v58, v214, v58, vcc
	v_cmp_le_i32_e32 vcc, v189, v64
	v_cmp_gt_i32_e64 s[0:1], v189, v188
	s_and_b64 vcc, vcc, s[0:1]
	v_add_u32_e32 v187, 19, v186
	v_cndmask_b32_e32 v42, v214, v42, vcc
	v_cmp_le_i32_e32 vcc, v187, v64
	v_cmp_gt_i32_e64 s[0:1], v187, v188
	v_add_u32_e32 v189, 51, v186
	s_and_b64 vcc, vcc, s[0:1]
	v_cndmask_b32_e32 v59, v214, v59, vcc
	v_cmp_le_i32_e32 vcc, v189, v64
	v_cmp_gt_i32_e64 s[0:1], v189, v188
	s_and_b64 vcc, vcc, s[0:1]
	v_add_u32_e32 v187, 24, v186
	v_cndmask_b32_e32 v43, v214, v43, vcc
	v_cmp_le_i32_e32 vcc, v187, v64
	v_cmp_gt_i32_e64 s[0:1], v187, v188
	v_add_u32_e32 v189, 56, v186
	s_and_b64 vcc, vcc, s[0:1]
	v_cndmask_b32_e32 v60, v214, v60, vcc
	v_cmp_le_i32_e32 vcc, v189, v64
	v_cmp_gt_i32_e64 s[0:1], v189, v188
	s_and_b64 vcc, vcc, s[0:1]
	v_add_u32_e32 v187, 25, v186
	v_cndmask_b32_e32 v44, v214, v44, vcc
	v_cmp_le_i32_e32 vcc, v187, v64
	v_cmp_gt_i32_e64 s[0:1], v187, v188
	v_add_u32_e32 v189, 57, v186
	s_and_b64 vcc, vcc, s[0:1]
	v_cndmask_b32_e32 v61, v214, v61, vcc
	v_cmp_le_i32_e32 vcc, v189, v64
	v_cmp_gt_i32_e64 s[0:1], v189, v188
	s_and_b64 vcc, vcc, s[0:1]
	v_add_u32_e32 v187, 26, v186
	v_cndmask_b32_e32 v45, v214, v45, vcc
	v_cmp_le_i32_e32 vcc, v187, v64
	v_cmp_gt_i32_e64 s[0:1], v187, v188
	v_add_u32_e32 v189, 58, v186
	s_and_b64 vcc, vcc, s[0:1]
	v_cndmask_b32_e32 v62, v214, v62, vcc
	v_cmp_le_i32_e32 vcc, v189, v64
	v_cmp_gt_i32_e64 s[0:1], v189, v188
	s_and_b64 vcc, vcc, s[0:1]
	v_add_u32_e32 v187, 27, v186
	v_cndmask_b32_e32 v46, v214, v46, vcc
	v_cmp_le_i32_e32 vcc, v187, v64
	v_cmp_gt_i32_e64 s[0:1], v187, v188
	v_add_u32_e32 v186, 59, v186
	s_and_b64 vcc, vcc, s[0:1]
	v_cndmask_b32_e32 v63, v214, v63, vcc
	v_cmp_le_i32_e32 vcc, v186, v64
	v_cmp_gt_i32_e64 s[0:1], v186, v188
	s_and_b64 vcc, vcc, s[0:1]
	v_cndmask_b32_e32 v47, v214, v47, vcc
	s_branch .LBB0_532

.LBB0_682:
	ds_bpermute_b32 v9, v0, v170
	ds_bpermute_b32 v0, v0, v171
	s_lshr_b32 s3, s6, 6
	s_add_i32 s3, s3, 1
	s_lshl_b64 s[4:5], -1, s3
	s_waitcnt lgkmcnt(1)
	v_or_b32_e32 v9, v9, v170
	s_waitcnt lgkmcnt(0)
	v_or_b32_e32 v0, v0, v171
	ds_bpermute_b32 v10, v1, v9
	ds_bpermute_b32 v1, v1, v0
	s_not_b64 s[4:5], s[4:5]
	s_cmpk_lt_u32 s6, 0xfc0
	s_cselect_b32 s5, s5, -1
	s_waitcnt lgkmcnt(1)
	v_or_b32_e32 v9, v10, v9
	s_waitcnt lgkmcnt(0)
	v_or_b32_e32 v0, v1, v0
	ds_bpermute_b32 v1, v2, v9
	ds_bpermute_b32 v2, v2, v0
	s_cselect_b32 s4, s4, -1
	s_waitcnt lgkmcnt(1)
	v_or_b32_e32 v1, v1, v9
	s_waitcnt lgkmcnt(0)
	v_or_b32_e32 v0, v2, v0
	ds_bpermute_b32 v2, v5, v1
	ds_bpermute_b32 v5, v5, v0
	s_waitcnt lgkmcnt(1)
	v_or_b32_e32 v1, v2, v1
	s_waitcnt lgkmcnt(0)
	v_or_b32_e32 v0, v5, v0
	ds_bpermute_b32 v2, v6, v1
	ds_bpermute_b32 v5, v6, v0
	s_waitcnt lgkmcnt(1)
	v_or_b32_e32 v1, v2, v1
	s_waitcnt lgkmcnt(0)
	v_or_b32_e32 v0, v5, v0
	ds_bpermute_b32 v2, v159, v1
	ds_bpermute_b32 v5, v159, v0
	s_waitcnt lgkmcnt(1)
	v_or_b32_e32 v1, v2, v1
	s_waitcnt lgkmcnt(0)
	v_or_b32_e32 v0, v5, v0
	v_readfirstlane_b32 s24, v1
	v_readfirstlane_b32 s25, v0
	s_and_b64 s[38:39], s[24:25], s[4:5]
	s_cmp_eq_u64 s[38:39], 0
	s_cbranch_scc1 .LBB0_689
	s_ff1_i32_b64 s3, s[38:39]
	s_lshl_b32 s50, s3, 13
	v_lshl_add_u64 v[0:1], v[162:163], 0, s[50:51]
	v_add_co_u32_e32 v10, vcc, 0x1000, v0
	v_max_f32_e32 v2, v4, v4
	s_nop 0
	v_addc_co_u32_e32 v11, vcc, 0, v1, vcc
	global_load_dwordx4 v[82:85], v[10:11], off offset:3072
	global_load_dwordx4 v[90:93], v[10:11], off offset:2048
	global_load_dwordx4 v[94:97], v[0:1], off offset:3072
	global_load_dwordx4 v[98:101], v[0:1], off offset:2048
	global_load_dwordx4 v[86:89], v[10:11], off offset:1024
	global_load_dwordx4 v[106:109], v[10:11], off
	global_load_dwordx4 v[102:105], v[0:1], off offset:1024
	global_load_dwordx4 v[110:113], v[0:1], off
	v_max_f32_e32 v0, v8, v8
	v_max_f32_e32 v1, v3, v3
	v_max_f32_e32 v0, v1, v0
	v_max_f32_e32 v1, v7, v7
	v_max_f32_e32 v1, v2, v1
	v_mul_f32_e32 v0, 0x413c5bb7, v0
	v_mov_b32_e32 v169, 0
	v_fmaak_f32 v172, v0, v1, 0x3d4ccccd
	v_sub_f32_e32 v232, 0, v172
	v_mov_b32_e32 v233, v232
	v_mov_b32_e32 v234, v232
	v_mov_b32_e32 v235, v232
	v_mov_b32_e32 v236, v232
	v_mov_b32_e32 v237, v232
	v_mov_b32_e32 v238, v232
	v_mov_b32_e32 v239, v232
	v_mov_b32_e32 v240, v232
	v_mov_b32_e32 v241, v232
	v_mov_b32_e32 v242, v232
	v_mov_b32_e32 v243, v232
	v_mov_b32_e32 v244, v232
	v_mov_b32_e32 v245, v232
	v_mov_b32_e32 v246, v232
	v_mov_b32_e32 v247, v232
	v_mov_b32_e32 v16, 0
	v_mov_b32_e32 v17, v169
	v_mov_b32_e32 v18, v169
	v_mov_b32_e32 v19, v169
	v_mov_b32_e32 v20, v169
	v_mov_b32_e32 v21, v169
	v_mov_b32_e32 v22, v169
	v_mov_b32_e32 v23, v169
	v_mov_b32_e32 v24, v169
	v_mov_b32_e32 v25, v169
	v_mov_b32_e32 v26, v169
	v_mov_b32_e32 v27, v169
	v_mov_b32_e32 v28, v169
	v_mov_b32_e32 v29, v169
	v_mov_b32_e32 v30, v169
	v_mov_b32_e32 v31, v169
	v_mov_b32_e32 v0, 0
	v_mov_b32_e32 v1, v169
	v_mov_b32_e32 v2, v169
	v_mov_b32_e32 v3, v169
	v_mov_b32_e32 v4, v169
	v_mov_b32_e32 v5, v169
	v_mov_b32_e32 v6, v169
	v_mov_b32_e32 v7, v169
	v_mov_b32_e32 v8, v169
	v_mov_b32_e32 v9, v169
	v_mov_b32_e32 v10, v169
	v_mov_b32_e32 v11, v169
	v_mov_b32_e32 v12, v169
	v_mov_b32_e32 v13, v169
	v_mov_b32_e32 v14, v169
	v_mov_b32_e32 v15, v169
	s_branch .LBB0_685
.LBB0_684:
	s_nop 6
	v_exp_f32_e32 v176, v32
	v_exp_f32_e32 v173, v48
	v_exp_f32_e32 v64, v49
	v_exp_f32_e32 v48, v33
	v_add_f32_e32 v49, v176, v173
	s_andn2_b64 vcc, exec, s[90:91]
	v_pk_add_f32 v[32:33], v[48:49], v[64:65]
	s_nop 0
	v_pk_add_f32 v[174:175], v[32:33], v[32:33] op_sel_hi:[0,1]
	v_exp_f32_e32 v49, v50
	v_exp_f32_e32 v177, v34
	v_exp_f32_e32 v174, v51
	v_exp_f32_e32 v50, v35
	v_add_f32_e32 v51, v177, v49
	v_pk_add_f32 v[32:33], v[50:51], v[174:175]
	s_nop 0
	v_pk_add_f32 v[34:35], v[32:33], v[32:33] op_sel_hi:[0,1]
	v_exp_f32_e32 v51, v52
	v_exp_f32_e32 v175, v36
	v_exp_f32_e32 v34, v53
	v_exp_f32_e32 v36, v37
	v_add_f32_e32 v37, v175, v51
	v_pk_add_f32 v[32:33], v[36:37], v[34:35]
	s_nop 0
	v_pk_add_f32 v[52:53], v[32:33], v[32:33] op_sel_hi:[0,1]
	v_exp_f32_e32 v35, v54
	v_exp_f32_e32 v37, v38
	v_exp_f32_e32 v52, v55
	v_exp_f32_e32 v38, v39
	v_add_f32_e32 v39, v37, v35
	v_cvt_pk_bf16_f32 v34, v51, v34
	v_cvt_pk_bf16_f32 v35, v35, v52
	v_pk_add_f32 v[32:33], v[38:39], v[52:53]
	s_nop 0
	v_pk_add_f32 v[54:55], v[32:33], v[32:33] op_sel_hi:[0,1]
	v_exp_f32_e32 v39, v56
	v_exp_f32_e32 v178, v40
	v_exp_f32_e32 v54, v57
	v_exp_f32_e32 v40, v41
	v_add_f32_e32 v41, v178, v39
	v_pk_add_f32 v[32:33], v[40:41], v[54:55]
	s_nop 0
	v_pk_add_f32 v[56:57], v[32:33], v[32:33] op_sel_hi:[0,1]
	v_exp_f32_e32 v41, v58
	v_exp_f32_e32 v55, v42
	v_exp_f32_e32 v56, v59
	v_exp_f32_e32 v42, v43
	v_add_f32_e32 v43, v55, v41
	v_pk_add_f32 v[32:33], v[42:43], v[56:57]
	s_nop 0
	v_pk_add_f32 v[58:59], v[32:33], v[32:33] op_sel_hi:[0,1]
	v_exp_f32_e32 v43, v60
	v_exp_f32_e32 v57, v44
	v_exp_f32_e32 v58, v61
	v_exp_f32_e32 v44, v45
	v_cvt_pk_bf16_f32 v32, v173, v64
	v_cvt_pk_bf16_f32 v33, v49, v174
	v_add_f32_e32 v45, v57, v43
	v_pk_add_f32 v[52:53], v[44:45], v[58:59]
	s_waitcnt vmcnt(15)
	v_mfma_f32_32x32x16_bf16 v[16:31], v[142:145], v[32:35], v[16:31]
	v_pk_add_f32 v[52:53], v[52:53], v[52:53] op_sel_hi:[0,1]
	v_exp_f32_e32 v45, v62
	s_waitcnt vmcnt(14)
	v_mfma_f32_32x32x16_bf16 v[0:15], v[138:141], v[32:35], v[0:15]
	v_exp_f32_e32 v52, v63
	v_cvt_pk_bf16_f32 v32, v39, v54
	v_cvt_pk_bf16_f32 v33, v41, v56
	v_cvt_pk_bf16_f32 v34, v43, v58
	v_cvt_pk_bf16_f32 v35, v45, v52
	s_waitcnt vmcnt(13)
	s_nop 0
	v_mfma_f32_32x32x16_bf16 v[16:31], v[134:137], v[32:35], v[16:31]
	s_waitcnt vmcnt(12)
	v_mfma_f32_32x32x16_bf16 v[0:15], v[130:133], v[32:35], v[0:15]
	v_cvt_pk_bf16_f32 v32, v176, v48
	v_cvt_pk_bf16_f32 v33, v177, v50
	v_cvt_pk_bf16_f32 v34, v175, v36
	v_cvt_pk_bf16_f32 v35, v37, v38
	v_exp_f32_e32 v37, v46
	s_waitcnt vmcnt(11)
	v_mfma_f32_32x32x16_bf16 v[16:31], v[126:129], v[32:35], v[16:31]
	s_waitcnt vmcnt(10)
	v_mfma_f32_32x32x16_bf16 v[0:15], v[122:125], v[32:35], v[0:15]
	v_exp_f32_e32 v36, v47
	v_cvt_pk_bf16_f32 v32, v178, v40
	v_cvt_pk_bf16_f32 v33, v55, v42
	v_cvt_pk_bf16_f32 v34, v57, v44
	v_cvt_pk_bf16_f32 v35, v37, v36
	v_add_f32_e32 v37, v37, v45
	v_pk_add_f32 v[36:37], v[36:37], v[52:53]
	s_waitcnt vmcnt(9)
	v_mfma_f32_32x32x16_bf16 v[16:31], v[118:121], v[32:35], v[16:31]
	v_add_f32_e32 v36, v36, v37
	v_add_f32_e32 v169, v169, v36
	s_waitcnt vmcnt(8)
	v_mfma_f32_32x32x16_bf16 v[0:15], v[114:117], v[32:35], v[0:15]
	s_cbranch_vccz .LBB0_690
.LBB0_685:
	s_waitcnt vmcnt(0)
	v_mfma_f32_32x32x16_bf16 v[48:63], v[110:113], v[66:69], v[232:247]
	s_add_u32 s4, s38, -1
	s_ff1_i32_b64 s3, s[38:39]
	s_addc_u32 s5, s39, -1
	s_and_b64 s[38:39], s[4:5], s[38:39]
	s_lshl_b32 s4, s3, 6
	s_lshl_b32 s50, s3, 13
	s_cmp_eq_u64 s[38:39], 0
	v_mfma_f32_32x32x16_bf16 v[32:47], v[106:109], v[66:69], v[232:247]
	v_mov_b64_e32 v[180:181], v[84:85]
	s_cselect_b64 s[90:91], -1, 0
	v_mov_b64_e32 v[178:179], v[82:83]
	v_lshl_add_u64 v[82:83], v[160:161], 0, s[50:51]
	s_ff1_i32_b64 s5, s[38:39]
	s_and_b64 s[24:25], s[90:91], exec
	global_load_dwordx4 v[142:145], v[82:83], off
	global_load_dwordx4 v[138:141], v[82:83], off offset:1024
	global_load_dwordx4 v[134:137], v[82:83], off offset:2048
	global_load_dwordx4 v[130:133], v[82:83], off offset:3072
	v_mfma_f32_32x32x16_bf16 v[48:63], v[102:105], v[70:73], v[48:63]
	v_add_co_u32_e32 v82, vcc, s77, v82
	s_cselect_b32 s5, s3, s5
	s_nop 0
	v_addc_co_u32_e32 v83, vcc, 0, v83, vcc
	s_lshl_b32 s50, s5, 13
	global_load_dwordx4 v[126:129], v[82:83], off
	global_load_dwordx4 v[122:125], v[82:83], off offset:1024
	global_load_dwordx4 v[118:121], v[82:83], off offset:2048
	global_load_dwordx4 v[114:117], v[82:83], off offset:3072
	v_mfma_f32_32x32x16_bf16 v[32:47], v[86:89], v[70:73], v[32:47]
	v_lshl_add_u64 v[82:83], v[162:163], 0, s[50:51]
	v_mov_b64_e32 v[176:177], v[96:97]
	v_add_co_u32_e32 v84, vcc, s77, v82
	v_mov_b64_e32 v[174:175], v[94:95]
	s_nop 0
	v_addc_co_u32_e32 v85, vcc, 0, v83, vcc
	v_mfma_f32_32x32x16_bf16 v[48:63], v[98:101], v[74:77], v[48:63]
	global_load_dwordx4 v[110:113], v[82:83], off
	global_load_dwordx4 v[102:105], v[82:83], off offset:1024
	global_load_dwordx4 v[106:109], v[84:85], off
	global_load_dwordx4 v[86:89], v[84:85], off offset:1024
	global_load_dwordx4 v[98:101], v[82:83], off offset:2048
	global_load_dwordx4 v[94:97], v[82:83], off offset:3072
	s_or_b32 s5, s4, 63
	s_cmp_le_u32 s5, s6
	v_mfma_f32_32x32x16_bf16 v[32:47], v[90:93], v[74:77], v[32:47]
	global_load_dwordx4 v[90:93], v[84:85], off offset:2048
	s_nop 0
	global_load_dwordx4 v[82:85], v[84:85], off offset:3072
	v_mfma_f32_32x32x16_bf16 v[48:63], v[174:177], v[78:81], v[48:63]
	v_mfma_f32_32x32x16_bf16 v[32:47], v[178:181], v[78:81], v[32:47]
	s_cbranch_scc1 .LBB0_687
	v_mov_b32_e32 v64, v228
	v_or_b32_e32 v173, s4, v152
	v_or_b32_e32 v174, s4, v153
	v_cmp_le_i32_e32 vcc, v173, v64
	v_or_b32_e32 v175, 2, v173
	v_or_b32_e32 v176, 2, v174
	s_nop 3
	v_cndmask_b32_e32 v48, v214, v48, vcc
	v_cmp_le_i32_e32 vcc, v174, v64
	s_nop 1
	v_cndmask_b32_e32 v32, v214, v32, vcc
	v_cmp_lt_i32_e32 vcc, v173, v64
	s_nop 1
	v_cndmask_b32_e32 v49, v214, v49, vcc
	v_cmp_lt_i32_e32 vcc, v174, v64
	s_nop 1
	v_cndmask_b32_e32 v33, v214, v33, vcc
	v_cmp_le_i32_e32 vcc, v175, v64
	v_or_b32_e32 v175, 3, v173
	s_nop 0
	v_cndmask_b32_e32 v50, v214, v50, vcc
	v_cmp_le_i32_e32 vcc, v176, v64
	v_or_b32_e32 v176, 3, v174
	s_nop 0
	v_cndmask_b32_e32 v34, v214, v34, vcc
	v_cmp_le_i32_e32 vcc, v175, v64
	v_or_b32_e32 v175, 8, v173
	s_nop 0
	v_cndmask_b32_e32 v51, v214, v51, vcc
	v_cmp_le_i32_e32 vcc, v176, v64
	v_or_b32_e32 v176, 8, v174
	s_nop 0
	v_cndmask_b32_e32 v35, v214, v35, vcc
	v_cmp_le_i32_e32 vcc, v175, v64
	v_or_b32_e32 v175, 9, v173
	s_nop 0
	v_cndmask_b32_e32 v52, v214, v52, vcc
	v_cmp_le_i32_e32 vcc, v176, v64
	v_or_b32_e32 v176, 9, v174
	s_nop 0
	v_cndmask_b32_e32 v36, v214, v36, vcc
	v_cmp_le_i32_e32 vcc, v175, v64
	v_or_b32_e32 v175, 10, v173
	s_nop 0
	v_cndmask_b32_e32 v53, v214, v53, vcc
	v_cmp_le_i32_e32 vcc, v176, v64
	v_or_b32_e32 v176, 10, v174
	s_nop 0
	v_cndmask_b32_e32 v37, v214, v37, vcc
	v_cmp_le_i32_e32 vcc, v175, v64
	v_or_b32_e32 v175, 11, v173
	s_nop 0
	v_cndmask_b32_e32 v54, v214, v54, vcc
	v_cmp_le_i32_e32 vcc, v176, v64
	v_or_b32_e32 v176, 11, v174
	s_nop 0
	v_cndmask_b32_e32 v38, v214, v38, vcc
	v_cmp_le_i32_e32 vcc, v175, v64
	v_or_b32_e32 v175, 16, v173
	s_nop 0
	v_cndmask_b32_e32 v55, v214, v55, vcc
	v_cmp_le_i32_e32 vcc, v176, v64
	v_or_b32_e32 v176, 16, v174
	s_nop 0
	v_cndmask_b32_e32 v39, v214, v39, vcc
	v_cmp_le_i32_e32 vcc, v175, v64
	v_or_b32_e32 v175, 17, v173
	s_nop 0
	v_cndmask_b32_e32 v56, v214, v56, vcc
	v_cmp_le_i32_e32 vcc, v176, v64
	v_or_b32_e32 v176, 17, v174
	s_nop 0
	v_cndmask_b32_e32 v40, v214, v40, vcc
	v_cmp_le_i32_e32 vcc, v175, v64
	v_or_b32_e32 v175, 18, v173
	s_nop 0
	v_cndmask_b32_e32 v57, v214, v57, vcc
	v_cmp_le_i32_e32 vcc, v176, v64
	v_or_b32_e32 v176, 18, v174
	s_nop 0
	v_cndmask_b32_e32 v41, v214, v41, vcc
	v_cmp_le_i32_e32 vcc, v175, v64
	v_or_b32_e32 v175, 19, v173
	s_nop 0
	v_cndmask_b32_e32 v58, v214, v58, vcc
	v_cmp_le_i32_e32 vcc, v176, v64
	v_or_b32_e32 v176, 19, v174
	s_nop 0
	v_cndmask_b32_e32 v42, v214, v42, vcc
	v_cmp_le_i32_e32 vcc, v175, v64
	v_or_b32_e32 v175, 24, v173
	s_nop 0
	v_cndmask_b32_e32 v59, v214, v59, vcc
	v_cmp_le_i32_e32 vcc, v176, v64
	v_or_b32_e32 v176, 24, v174
	s_nop 0
	v_cndmask_b32_e32 v43, v214, v43, vcc
	v_cmp_le_i32_e32 vcc, v175, v64
	v_or_b32_e32 v175, 25, v173
	s_nop 0
	v_cndmask_b32_e32 v60, v214, v60, vcc
	v_cmp_le_i32_e32 vcc, v176, v64
	v_or_b32_e32 v176, 25, v174
	s_nop 0
	v_cndmask_b32_e32 v44, v214, v44, vcc
	v_cmp_le_i32_e32 vcc, v175, v64
	v_or_b32_e32 v175, 26, v173
	v_or_b32_e32 v173, 27, v173
	v_cndmask_b32_e32 v61, v214, v61, vcc
	v_cmp_le_i32_e32 vcc, v176, v64
	v_or_b32_e32 v176, 26, v174
	v_or_b32_e32 v174, 27, v174
	v_cndmask_b32_e32 v45, v214, v45, vcc
	v_cmp_le_i32_e32 vcc, v175, v64
	s_nop 1
	v_cndmask_b32_e32 v62, v214, v62, vcc
	v_cmp_le_i32_e32 vcc, v176, v64
	s_nop 1
	v_cndmask_b32_e32 v46, v214, v46, vcc
	v_cmp_le_i32_e32 vcc, v173, v64
	s_nop 1
	v_cndmask_b32_e32 v63, v214, v63, vcc
	v_cmp_le_i32_e32 vcc, v174, v64
	s_nop 1
	v_cndmask_b32_e32 v47, v214, v47, vcc
